# row passes P4/P8: removed the four vmcnt(0) that serialised the first row's bf16-source chunk loads (register-reuse guards for the other, mutually exclusive, f32-slab path)
# speedup vs baseline: 1.0077x; 1.0077x over previous
; template <int RB, int XB>
; __device__ __forceinline__ void row_op2(const RowPtrs (&r)[NR], bool has_src, const float* gpost, const float* gnext, int lane) {
;     ...
;     if (has_src) {
;         u32x2 sb[NR][4];
; #pragma unroll
;         for (int k = 0; k < NR; ++k)
; #pragma unroll
;             for (int j = 0; j < 4; ++j) {
;                 if (r[k].srcf != nullptr) { const float* sf = r[k].srcf; s[k][j] = ((const f32x4*)sf)[lane + 64 * j];
;                     if (r[k].parts4) s[k][j] = (s[k][j] + ((const f32x4*)(sf + (size_t)TS * D))[lane + 64 * j]) + (((const f32x4*)(sf + (size_t)2 * TS * D))[lane + 64 * j] + ((const f32x4*)(sf + (size_t)3 * TS * D))[lane + 64 * j]); }
;                 else sb[k][j] = ((const u32x2*)r[k].srcb)[lane + 64 * j];
.LBB0_535:
	s_andn2_b64 vcc, exec, s[8:9]
	v_lshl_add_u64 v[110:111], s[58:59], 0, v[134:135]
	s_cbranch_vccnz .LBB0_537
	v_add_co_u32_e32 v48, vcc, 0xa300000, v110
	s_nop 1
	v_addc_co_u32_e32 v49, vcc, 0, v111, vcc
	global_load_dwordx2 v[112:113], v[48:49], off

; template <int RB, int XB>
; __device__ __forceinline__ void row_op2(const RowPtrs (&r)[NR], bool has_src, const float* gpost, const float* gnext, int lane) {
;     ...
;             for (int j = 0; j < 4; ++j) {
;                 if (r[k].srcf != nullptr) { const float* sf = r[k].srcf; s[k][j] = ((const f32x4*)sf)[lane + 64 * j];
;                     if (r[k].parts4) s[k][j] = (s[k][j] + ((const f32x4*)(sf + (size_t)TS * D))[lane + 64 * j]) + (((const f32x4*)(sf + (size_t)2 * TS * D))[lane + 64 * j] + ((const f32x4*)(sf + (size_t)3 * TS * D))[lane + 64 * j]); }
;                 else sb[k][j] = ((const u32x2*)r[k].srcb)[lane + 64 * j];
.LBB0_550:
	v_add_co_u32_e32 v52, vcc, 0xa300000, v110
	s_nop 1
	v_addc_co_u32_e32 v53, vcc, 0, v111, vcc
	global_load_dwordx2 v[114:115], v[52:53], off offset:512
	s_and_b64 vcc, exec, s[8:9]
	s_mov_b64 s[84:85], -1
	s_cbranch_vccz .LBB0_542

; template <int RB, int XB>
; __device__ __forceinline__ void row_op2(const RowPtrs (&r)[NR], bool has_src, const float* gpost, const float* gnext, int lane) {
;     ...
;             for (int j = 0; j < 4; ++j) {
;                 if (r[k].srcf != nullptr) { const float* sf = r[k].srcf; s[k][j] = ((const f32x4*)sf)[lane + 64 * j];
;                     if (r[k].parts4) s[k][j] = (s[k][j] + ((const f32x4*)(sf + (size_t)TS * D))[lane + 64 * j]) + (((const f32x4*)(sf + (size_t)2 * TS * D))[lane + 64 * j] + ((const f32x4*)(sf + (size_t)3 * TS * D))[lane + 64 * j]); }
;                 else sb[k][j] = ((const u32x2*)r[k].srcb)[lane + 64 * j];
.LBB0_552:
	v_add_co_u32_e32 v56, vcc, 0xa300000, v110
	s_nop 1
	v_addc_co_u32_e32 v57, vcc, 0, v111, vcc
	global_load_dwordx2 v[116:117], v[56:57], off offset:1024
	s_and_b64 vcc, exec, s[8:9]
	s_mov_b64 s[8:9], -1
	s_cbranch_vccz .LBB0_546

; template <int RB, int XB>
; __device__ __forceinline__ void row_op2(const RowPtrs (&r)[NR], bool has_src, const float* gpost, const float* gnext, int lane) {
;     ...
;             for (int j = 0; j < 4; ++j) {
;                 if (r[k].srcf != nullptr) { const float* sf = r[k].srcf; s[k][j] = ((const f32x4*)sf)[lane + 64 * j];
;                     if (r[k].parts4) s[k][j] = (s[k][j] + ((const f32x4*)(sf + (size_t)TS * D))[lane + 64 * j]) + (((const f32x4*)(sf + (size_t)2 * TS * D))[lane + 64 * j] + ((const f32x4*)(sf + (size_t)3 * TS * D))[lane + 64 * j]); }
;                 else sb[k][j] = ((const u32x2*)r[k].srcb)[lane + 64 * j];
.LBB0_554:
	v_add_co_u32_e32 v60, vcc, 0xa300000, v110
	s_nop 1
	v_addc_co_u32_e32 v61, vcc, 0, v111, vcc
	global_load_dwordx2 v[118:119], v[60:61], off offset:1536

; template <int RB, int XB>
; __device__ __forceinline__ void row_op2(const RowPtrs (&r)[NR], bool has_src, const float* gpost, const float* gnext, int lane) {
;     ...
;     if (has_src) {
;         u32x2 sb[NR][4];
; #pragma unroll
;         for (int k = 0; k < NR; ++k)
; #pragma unroll
;             for (int j = 0; j < 4; ++j) {
;                 if (r[k].srcf != nullptr) { const float* sf = r[k].srcf; s[k][j] = ((const f32x4*)sf)[lane + 64 * j];
;                     if (r[k].parts4) s[k][j] = (s[k][j] + ((const f32x4*)(sf + (size_t)TS * D))[lane + 64 * j]) + (((const f32x4*)(sf + (size_t)2 * TS * D))[lane + 64 * j] + ((const f32x4*)(sf + (size_t)3 * TS * D))[lane + 64 * j]); }
;                 else sb[k][j] = ((const u32x2*)r[k].srcb)[lane + 64 * j];
.LBB0_991:
	s_andn2_b64 vcc, exec, s[8:9]
	v_lshl_add_u64 v[62:63], s[36:37], 0, v[134:135]
	s_cbranch_vccnz .LBB0_993
	v_add_co_u32_e32 v0, vcc, 0x1c00000, v62
	s_nop 1
	v_addc_co_u32_e32 v1, vcc, 0, v63, vcc
	global_load_dwordx2 v[88:89], v[0:1], off

; template <int RB, int XB>
; __device__ __forceinline__ void row_op2(const RowPtrs (&r)[NR], bool has_src, const float* gpost, const float* gnext, int lane) {
;     ...
;             for (int j = 0; j < 4; ++j) {
;                 if (r[k].srcf != nullptr) { const float* sf = r[k].srcf; s[k][j] = ((const f32x4*)sf)[lane + 64 * j];
;                     if (r[k].parts4) s[k][j] = (s[k][j] + ((const f32x4*)(sf + (size_t)TS * D))[lane + 64 * j]) + (((const f32x4*)(sf + (size_t)2 * TS * D))[lane + 64 * j] + ((const f32x4*)(sf + (size_t)3 * TS * D))[lane + 64 * j]); }
;                 else sb[k][j] = ((const u32x2*)r[k].srcb)[lane + 64 * j];
.LBB0_1006:
	v_add_co_u32_e32 v4, vcc, 0x1c00000, v62
	s_nop 1
	v_addc_co_u32_e32 v5, vcc, 0, v63, vcc
	global_load_dwordx2 v[90:91], v[4:5], off offset:512
	s_and_b64 vcc, exec, s[8:9]
	s_mov_b64 s[54:55], -1
	s_cbranch_vccz .LBB0_998

; template <int RB, int XB>
; __device__ __forceinline__ void row_op2(const RowPtrs (&r)[NR], bool has_src, const float* gpost, const float* gnext, int lane) {
;     ...
;             for (int j = 0; j < 4; ++j) {
;                 if (r[k].srcf != nullptr) { const float* sf = r[k].srcf; s[k][j] = ((const f32x4*)sf)[lane + 64 * j];
;                     if (r[k].parts4) s[k][j] = (s[k][j] + ((const f32x4*)(sf + (size_t)TS * D))[lane + 64 * j]) + (((const f32x4*)(sf + (size_t)2 * TS * D))[lane + 64 * j] + ((const f32x4*)(sf + (size_t)3 * TS * D))[lane + 64 * j]); }
;                 else sb[k][j] = ((const u32x2*)r[k].srcb)[lane + 64 * j];
.LBB0_1008:
	v_add_co_u32_e32 v8, vcc, 0x1c00000, v62
	s_nop 1
	v_addc_co_u32_e32 v9, vcc, 0, v63, vcc
	global_load_dwordx2 v[92:93], v[8:9], off offset:1024
	s_and_b64 vcc, exec, s[8:9]
	s_mov_b64 s[8:9], -1
	s_cbranch_vccz .LBB0_1002

; template <int RB, int XB>
; __device__ __forceinline__ void row_op2(const RowPtrs (&r)[NR], bool has_src, const float* gpost, const float* gnext, int lane) {
;     ...
;             for (int j = 0; j < 4; ++j) {
;                 if (r[k].srcf != nullptr) { const float* sf = r[k].srcf; s[k][j] = ((const f32x4*)sf)[lane + 64 * j];
;                     if (r[k].parts4) s[k][j] = (s[k][j] + ((const f32x4*)(sf + (size_t)TS * D))[lane + 64 * j]) + (((const f32x4*)(sf + (size_t)2 * TS * D))[lane + 64 * j] + ((const f32x4*)(sf + (size_t)3 * TS * D))[lane + 64 * j]); }
;                 else sb[k][j] = ((const u32x2*)r[k].srcb)[lane + 64 * j];
.LBB0_1010:
	v_add_co_u32_e32 v12, vcc, 0x1c00000, v62
	s_nop 1
	v_addc_co_u32_e32 v13, vcc, 0, v63, vcc
	global_load_dwordx2 v[94:95], v[12:13], off offset:1536
